# adds: P2 share of late weight conversions moved to P4 idle workgroups (LRU side of P2 was critical)
# speedup vs baseline: 1.0247x; 1.0045x over previous
; #define LAS __attribute__((address_space(3)))
; __device__ __forceinline__ void late_range(const Args& a, LAS unsigned char* lds, int lo, int hi, int w, int nw, int wave, int lane) {
;     LAS float* scr = (LAS float*)(lds + wave * 16384);
;     for (int it = lo + w; it < hi; it += nw) late_item(a, it, scr, lane);
; __global__ void __launch_bounds__(NTHR, LB2) hymba_fwd(Args a) {
;     ...
;         { const int t2 = my_tid(); late_range(a, lds, N_LATE_P1, N_LATE_P2, (cL - 128) * NWAVES + (t2 >> 6), 128 * NWAVES, __builtin_amdgcn_readfirstlane(t2 >> 6), t2 & 63); } } }
.LBB0_800:
	s_getreg_b32 s0, hwreg(HW_REG_HW_ID, 0, 6)
	s_lshl_b32 s0, s0, 2
	s_and_b32 s0, s0, 0xfc
	s_or_b32 s0, s0, 0x23f00
	v_mov_b32_e32 v0, s0
	s_waitcnt lgkmcnt(0)
	ds_read_b32 v1, v0
	v_mbcnt_lo_u32_b32 v0, -1, 0
	v_mbcnt_hi_u32_b32 v0, -1, v0
	s_waitcnt lgkmcnt(0)
	v_readfirstlane_b32 s0, v1
	s_nop 1
	v_lshl_add_u32 v1, s0, 6, v0
	v_ashrrev_i32_e32 v2, 6, v1
	v_lshl_add_u32 v1, s5, 3, v2
	s_movk_i32 s0, 0x0
	v_readfirstlane_b32 s4, v2
	v_cmp_gt_i32_e32 vcc, s0, v1
	s_and_saveexec_b64 s[0:1], vcc
	s_cbranch_execz .LBB0_855
	v_add_u32_e32 v62, 0x1600, v1
	v_bfe_u32 v36, v0, 3, 3
	v_lshlrev_b32_e32 v1, 4, v0
	v_lshlrev_b32_e32 v0, 3, v0
	s_lshl_b32 s4, s4, 14
	v_and_b32_e32 v0, 56, v0
	s_add_i32 s4, s4, 0
	v_and_b32_e32 v38, 0x70, v1
	v_mul_u32_u24_e32 v1, 0x84, v0
	v_lshlrev_b32_e32 v2, 2, v36
	v_readlane_b32 s12, v252, 0
	v_readlane_b32 s36, v252, 40
	v_add_u32_e32 v63, s4, v38
	v_add3_u32 v68, s4, v1, v2
	v_mov_b32_e32 v39, 0
	v_readlane_b32 s14, v252, 2
	v_readlane_b32 s15, v252, 3
	v_readlane_b32 s37, v252, 41
	v_readlane_b32 s42, v252, 46
	v_readlane_b32 s43, v252, 47
	v_readlane_b32 s50, v252, 54
	v_readlane_b32 s51, v252, 55
	v_readlane_b32 s4, v252, 58
	v_lshl_add_u64 v[40:41], s[14:15], 0, v[38:39]
	v_lshl_add_u64 v[42:43], s[50:51], 0, v[38:39]
	v_lshl_add_u64 v[44:45], s[42:43], 0, v[38:39]
	v_lshl_add_u64 v[46:47], s[36:37], 0, v[38:39]
	v_lshlrev_b32_e32 v38, 1, v0
	v_readlane_b32 s5, v252, 59
	v_or_b32_e32 v1, 32, v36
	v_mul_u32_u24_e32 v64, 0x84, v36
	v_lshl_add_u64 v[48:49], s[4:5], 0, v[38:39]
	v_readlane_b32 s4, v252, 60
	v_readlane_b32 s5, v252, 61
	v_or_b32_e32 v65, 8, v36
	v_or_b32_e32 v66, 16, v36
	v_lshl_add_u64 v[50:51], s[4:5], 0, v[38:39]
	v_readlane_b32 s4, v251, 57
	v_readlane_b32 s5, v251, 58
	v_or_b32_e32 v67, 24, v36
	v_mul_u32_u24_e32 v69, 0x84, v1
	v_lshl_add_u64 v[52:53], s[4:5], 0, v[38:39]
	v_readlane_b32 s4, v252, 63
	v_readlane_b32 s5, v251, 0
	v_mov_b32_e32 v37, v39
	v_lshlrev_b32_e32 v70, 6, v62
	v_lshl_add_u64 v[54:55], s[4:5], 0, v[38:39]
	v_readlane_b32 s4, v251, 50
	v_readlane_b32 s5, v251, 51
	v_lshlrev_b32_e32 v71, 2, v62
	s_mov_b64 s[14:15], 0
	v_cndmask_b32_e64 v0, 0, 1, s[4:5]
	v_cmp_ne_u32_e64 s[34:35], 1, v0
	s_movk_i32 s4, 0x7fff
	s_mov_b32 s5, 0xffff0000
	v_readlane_b32 s13, v252, 1
	v_readlane_b32 s16, v252, 4
	v_readlane_b32 s17, v252, 5
	v_readlane_b32 s18, v252, 6
	v_readlane_b32 s19, v252, 7
	v_readlane_b32 s38, v252, 42
	v_readlane_b32 s39, v252, 43
	v_readlane_b32 s40, v252, 44
	v_readlane_b32 s41, v252, 45
	v_readlane_b32 s44, v252, 48
	v_readlane_b32 s45, v252, 49
	v_readlane_b32 s46, v252, 50
	v_readlane_b32 s47, v252, 51
	v_readlane_b32 s48, v252, 52
	v_readlane_b32 s49, v252, 53
	s_branch .LBB0_804

; __device__ __forceinline__ void late_range(const Args& a, LAS unsigned char* lds, int lo, int hi, int w, int nw, int wave, int lane) {
;     ...
;     for (int it = lo + w; it < hi; it += nw) late_item(a, it, scr, lane);
.LBB0_803:
	s_or_b64 exec, exec, s[12:13]
	s_movk_i32 s6, 0x11ff
	v_add_u32_e32 v0, 0x400, v62
	v_cmp_lt_i32_e32 vcc, s6, v62
	v_add_u32_e32 v70, 0x10000, v70
	v_add_u32_e32 v71, 0x1000, v71
	s_or_b64 s[14:15], vcc, s[14:15]
	v_mov_b32_e32 v62, v0
	s_andn2_b64 exec, exec, s[14:15]
	s_cbranch_execz .LBB0_855

; #define LAS __attribute__((address_space(3)))
; __device__ __forceinline__ void late_range(const Args& a, LAS unsigned char* lds, int lo, int hi, int w, int nw, int wave, int lane) {
;     LAS float* scr = (LAS float*)(lds + wave * 16384);
;     for (int it = lo + w; it < hi; it += nw) late_item(a, it, scr, lane);
; __global__ void __launch_bounds__(NTHR, LB2) hymba_fwd(Args a) {
;     ...
;             if (c >= 64 && c < 240) { const int t2 = my_tid(); late_range(a, lds, N_LATE_P2, N_LATE, (c - 64) * NWAVES + (t2 >> 6), 176 * NWAVES, __builtin_amdgcn_readfirstlane(t2 >> 6), t2 & 63); } }
.LBB0_1406:
	s_getreg_b32 s0, hwreg(HW_REG_HW_ID, 0, 6)
	s_lshl_b32 s0, s0, 2
	s_and_b32 s0, s0, 0xfc
	s_or_b32 s0, s0, 0x23f00
	v_mov_b32_e32 v0, s0
	ds_read_b32 v1, v0
	v_readlane_b32 s0, v250, 4
	v_mbcnt_lo_u32_b32 v0, -1, 0
	v_mbcnt_hi_u32_b32 v0, -1, v0
	s_addk_i32 s0, 0xfe00
	s_waitcnt lgkmcnt(0)
	v_readfirstlane_b32 s1, v1
	s_nop 1
	v_lshl_add_u32 v1, s1, 6, v0
	v_ashrrev_i32_e32 v2, 6, v1
	v_add_u32_e32 v1, s0, v2
	s_movk_i32 s0, 0x3800
	v_readfirstlane_b32 s4, v2
	v_cmp_gt_i32_e32 vcc, s0, v1
	s_and_saveexec_b64 s[0:1], vcc
	s_cbranch_execz .LBB0_1465
	v_add_u32_e32 v66, 0x1600, v1
	v_bfe_u32 v36, v0, 3, 3
	v_lshlrev_b32_e32 v1, 4, v0
	v_lshlrev_b32_e32 v0, 3, v0
	s_lshl_b32 s4, s4, 14
	v_and_b32_e32 v0, 56, v0
	s_add_i32 s4, s4, 0
	v_and_b32_e32 v38, 0x70, v1
	v_mul_u32_u24_e32 v1, 0x84, v0
	v_lshlrev_b32_e32 v3, 2, v36
	v_add_u32_e32 v67, s4, v38
	v_add3_u32 v71, s4, v1, v3
	v_or_b32_e32 v1, 32, v36
	v_mov_b32_e32 v39, 0
	v_readlane_b32 s4, v252, 60
	v_mul_u32_u24_e32 v72, 0x84, v1
	v_readlane_b32 s12, v252, 0
	v_readlane_b32 s56, v252, 40
	v_lshlrev_b32_e32 v0, 1, v0
	v_mov_b32_e32 v1, v39
	v_readlane_b32 s5, v252, 61
	v_mul_u32_u24_e32 v2, 0x84, v36
	v_readlane_b32 s16, v252, 4
	v_readlane_b32 s17, v252, 5
	v_readlane_b32 s18, v252, 6
	v_readlane_b32 s19, v252, 7
	v_readlane_b32 s57, v252, 41
	v_readlane_b32 s62, v252, 46
	v_readlane_b32 s63, v252, 47
	v_readlane_b32 s70, v252, 54
	v_readlane_b32 s71, v252, 55
	v_lshl_add_u64 v[56:57], s[4:5], 0, v[0:1]
	v_readlane_b32 s4, v252, 63
	v_readlane_b32 s14, v252, 2
	v_readlane_b32 s15, v252, 3
	v_lshl_add_u64 v[40:41], s[16:17], 0, v[38:39]
	v_readlane_b32 s58, v252, 42
	v_readlane_b32 s59, v252, 43
	s_mov_b64 s[16:17], s[56:57]
	s_mov_b64 s[22:23], s[62:63]
	s_mov_b64 s[30:31], s[70:71]
	v_readlane_b32 s5, v251, 0
	v_add_u32_e32 v75, v67, v2
	v_or_b32_e32 v68, 8, v36
	v_or_b32_e32 v69, 16, v36
	v_or_b32_e32 v70, 24, v36
	v_lshl_add_u64 v[42:43], s[14:15], 0, v[38:39]
	v_lshl_add_u64 v[44:45], s[30:31], 0, v[38:39]
	v_lshl_add_u64 v[46:47], s[22:23], 0, v[38:39]
	v_lshl_add_u64 v[48:49], s[52:53], 0, v[0:1]
	v_lshl_add_u64 v[50:51], s[16:17], 0, v[38:39]
	v_lshl_add_u64 v[52:53], s[86:87], 0, v[0:1]
	v_lshl_add_u64 v[54:55], s[90:91], 0, v[0:1]
	v_lshl_add_u64 v[58:59], s[4:5], 0, v[0:1]
	v_mov_b32_e32 v37, v39
	v_lshlrev_b32_e32 v73, 6, v66
	v_lshlrev_b32_e32 v74, 2, v66
	s_mov_b64 s[14:15], 0
	s_mov_b32 s4, 0x10000
	v_add_u32_e32 v76, 0x420, v75
	v_add_u32_e32 v77, 0x428, v75
	v_add_u32_e32 v78, 0x840, v75
	v_add_u32_e32 v79, 0x848, v75
	v_add_u32_e32 v80, 0xc60, v75
	v_add_u32_e32 v81, 0xc68, v75
	v_add_u32_e32 v82, 0x1080, v75
	v_add_u32_e32 v83, 0x1088, v75
	v_add_u32_e32 v84, 0x14a0, v75
	v_add_u32_e32 v85, 0x14a8, v75
	v_add_u32_e32 v86, 0x18c0, v75
	v_add_u32_e32 v87, 0x18c8, v75
	v_add_u32_e32 v88, 0x1ce0, v75
	s_movk_i32 s5, 0x7fff
	s_mov_b32 s6, 0xffff0000
	v_add_u32_e32 v89, 0x1ce8, v75
	v_readlane_b32 s13, v252, 1
	v_readlane_b32 s60, v252, 44
	v_readlane_b32 s61, v252, 45
	v_readlane_b32 s64, v252, 48
	v_readlane_b32 s65, v252, 49
	v_readlane_b32 s66, v252, 50
	v_readlane_b32 s67, v252, 51
	v_readlane_b32 s68, v252, 52
	v_readlane_b32 s69, v252, 53
	s_mov_b64 s[18:19], s[58:59]
	s_branch .LBB0_1410
